# GU: row-scale (ss) loads issued in the peeled first load segment into VGPRs the K-loop never touches; epilogue starts without a load round trip
# baseline (speedup 1.0000x reference)
; #define PG8_STAGE(bufoff, gbase, voff) do { _Pragma("unroll") for (int _i = 0; _i < 2; ++_i) \
;         __builtin_amdgcn_global_load_lds((const unsigned*)((const char*)(gbase) + (voff)[_i]), (PG8_LAS unsigned*)(lds + (bufoff) + ldsw + _i * 8192), 16, 0, 0); } while (0)
; #define PG8_LDA(dst, b, h) do { _Pragma("unroll") for (int m = 0; m < 4; ++m) _Pragma("unroll") for (int k = 0; k < 2; ++k) dst[m][k] = *(const PG8_LAS bf16x8*)(lds + PG8_SA(b, h) + aoff + m * 2048 + k * 1024); } while (0)
; #define PG8_LDB(dst, b, h) do { _Pragma("unroll") for (int n = 0; n < 2; ++n) _Pragma("unroll") for (int k = 0; k < 2; ++k) dst[n][k] = *(const PG8_LAS bf16x8*)(lds + PG8_SB(b, h) + boff + n * 2048 + k * 1024); } while (0)
; #define PG8_MMA(ai, bj, At, Bt) do { __builtin_amdgcn_s_setprio(1); _Pragma("unroll") for (int m = 0; m < 4; ++m) _Pragma("unroll") for (int n = 0; n < 2; ++n) _Pragma("unroll") for (int k = 0; k < 2; ++k) \
;         acc[ai][bj][m][n] = __builtin_amdgcn_mfma_f32_16x16x32_bf16(Bt[n][k], At[m][k], acc[ai][bj][m][n], 0, 0, 0); __builtin_amdgcn_s_setprio(0); } while (0)
; #define PG8_WAIT_V(n) asm volatile("s_waitcnt vmcnt(" #n ")" ::: "memory")
; #define PG8_BAR __builtin_amdgcn_s_barrier()
; template <class Epi, class Sched, bool ALIGN_EPI = false, bool SP2 = false>
; __device__ __forceinline__ void gemm_phase(PG8_LAS unsigned char* lds, const Gemm g, const Sched& S, const Epi& E, const int wave_s) {
;     ...
;         const char* nA = has_next ? (const char*)g.A + (size_t)nxt.pm * tstep + (size_t)nxt.k0 * kstep : cA; const char* nB = has_next ? (const char*)g.Bt + (size_t)nxt.pn * tstep + (size_t)nxt.k0 * kstep : cB;
;     ...
;             PG8_LDB(B0, 0, 0); PG8_LDB(B1, 0, 1); PG8_SCHED; PG8_LDA(At, 0, 0); PG8_STAGE(PG8_SA(1, 1), a1 + hstep, voffA);
;             PG8_WAIT_V(8); PG8_WAIT_L(0); PG8_BAR; PG8_MMA(0, 0, At, B0); PG8_MMA(0, 1, At, B1); PG8_BAR; PG8_SCHED;
;             PG8_LDA(At, 0, 1); PG8_STAGE(PG8_SB(0, 0), b2, voffB); PG8_STAGE(PG8_SB(0, 1), b2 + hstep, voffB); PG8_STAGE(PG8_SA(0, 0), a2, voffA);
;             PG8_WAIT_V(8); PG8_WAIT_L(0); PG8_BAR; PG8_MMA(1, 0, At, B0); PG8_MMA(1, 1, At, B1); PG8_BAR; PG8_SCHED;
;     __device__ __forceinline__ void operator()(const f32x4 (&acc)[2][2][4][2], const pg8::Unit& u, int wr, int wc, int fr, int fq) const {
;     ...
;             for (int m = 0; m < 4; ++m) rs[ai][m] = ss[row0 + ai * 128 + m * 16];
.Lgum_522:
	s_ashr_i32 s19, s18, 31
	s_lshl_b64 s[20:21], s[18:19], 19
	s_add_u32 s20, s28, s20
	s_addc_u32 s21, s29, s21
	s_and_b64 s[22:23], s[6:7], exec
	s_cselect_b32 s19, s21, s25
	s_cselect_b32 s46, s20, s24
	s_ashr_i32 s17, s16, 31
	s_lshl_b64 s[22:23], s[16:17], 19
	s_add_u32 s22, s30, s22
	s_addc_u32 s23, s31, s23
	s_and_b64 s[100:101], s[6:7], exec
	s_cselect_b32 s17, s23, s49
	s_cselect_b32 s47, s22, s48
	s_lshl_b32 s100, s45, 8
	s_add_i32 s100, s100, s39
	v_add_u32_e32 v251, s100, v145
	v_lshlrev_b32_e32 v251, 2, v251
	global_load_dword v206, v251, s[12:13]
	global_load_dword v207, v251, s[12:13] offset:64
	global_load_dword v246, v251, s[12:13] offset:128
	global_load_dword v247, v251, s[12:13] offset:192
	global_load_dword v248, v251, s[12:13] offset:512
	global_load_dword v249, v251, s[12:13] offset:576
	global_load_dword v250, v251, s[12:13] offset:640
	global_load_dword v251, v251, s[12:13] offset:704
	s_waitcnt vmcnt(16)
	s_waitcnt lgkmcnt(0)
	s_barrier
	s_setprio 1
	s_waitcnt lgkmcnt(0)
	v_mfma_f32_16x16x32_bf16 v[124:127], v[140:143], v[190:193], 0
	v_mfma_f32_16x16x32_bf16 v[116:119], v[154:157], v[190:193], 0
	v_mfma_f32_16x16x32_bf16 v[108:111], v[140:143], v[214:217], 0
	v_mfma_f32_16x16x32_bf16 v[100:103], v[154:157], v[214:217], 0
	v_mfma_f32_16x16x32_bf16 v[92:95], v[140:143], v[222:225], 0
	v_mfma_f32_16x16x32_bf16 v[84:87], v[154:157], v[222:225], 0
	v_mfma_f32_16x16x32_bf16 v[76:79], v[140:143], v[230:233], 0
	v_mfma_f32_16x16x32_bf16 v[68:71], v[154:157], v[230:233], 0
	v_mfma_f32_16x16x32_bf16 v[124:127], v[150:153], v[210:213], v[124:127]
	v_mfma_f32_16x16x32_bf16 v[116:119], v[158:161], v[210:213], v[116:119]
	v_mfma_f32_16x16x32_bf16 v[108:111], v[150:153], v[218:221], v[108:111]
	v_mfma_f32_16x16x32_bf16 v[100:103], v[158:161], v[218:221], v[100:103]
	v_mfma_f32_16x16x32_bf16 v[92:95], v[150:153], v[226:229], v[92:95]
	v_mfma_f32_16x16x32_bf16 v[84:87], v[158:161], v[226:229], v[84:87]
	v_mfma_f32_16x16x32_bf16 v[76:79], v[150:153], v[234:237], v[76:79]
	v_mfma_f32_16x16x32_bf16 v[68:71], v[158:161], v[234:237], v[68:71]
	s_setprio 0
	s_setprio 1
	v_mfma_f32_16x16x32_bf16 v[120:123], v[174:177], v[190:193], 0
	v_mfma_f32_16x16x32_bf16 v[112:115], v[182:185], v[190:193], 0
	v_mfma_f32_16x16x32_bf16 v[104:107], v[174:177], v[214:217], 0
	v_mfma_f32_16x16x32_bf16 v[96:99], v[182:185], v[214:217], 0
	v_mfma_f32_16x16x32_bf16 v[88:91], v[174:177], v[222:225], 0
	v_mfma_f32_16x16x32_bf16 v[80:83], v[182:185], v[222:225], 0
	v_mfma_f32_16x16x32_bf16 v[72:75], v[174:177], v[230:233], 0
	v_mfma_f32_16x16x32_bf16 v[64:67], v[182:185], v[230:233], 0
	v_mfma_f32_16x16x32_bf16 v[120:123], v[178:181], v[210:213], v[120:123]
	v_mfma_f32_16x16x32_bf16 v[112:115], v[186:189], v[210:213], v[112:115]
	v_mfma_f32_16x16x32_bf16 v[104:107], v[178:181], v[218:221], v[104:107]
	v_mfma_f32_16x16x32_bf16 v[96:99], v[186:189], v[218:221], v[96:99]
	v_mfma_f32_16x16x32_bf16 v[88:91], v[178:181], v[226:229], v[88:91]
	v_mfma_f32_16x16x32_bf16 v[80:83], v[186:189], v[226:229], v[80:83]
	v_mfma_f32_16x16x32_bf16 v[72:75], v[178:181], v[234:237], v[72:75]
	v_mfma_f32_16x16x32_bf16 v[64:67], v[186:189], v[234:237], v[64:67]
	s_setprio 0
	s_barrier
	s_add_i32 s51, s51, s34
	v_lshl_add_u64 v[194:195], s[2:3], 0, v[128:129]
	s_mov_b32 m0, s51
	ds_read_b128 v[190:193], v148 offset:16384
	ds_read_b128 v[210:213], v148 offset:17408
	ds_read_b128 v[214:217], v148 offset:18432
	ds_read_b128 v[218:221], v148 offset:19456
	ds_read_b128 v[222:225], v148 offset:20480
	ds_read_b128 v[226:229], v148 offset:21504
	ds_read_b128 v[230:233], v148 offset:22528
	ds_read_b128 v[234:237], v148 offset:23552
	global_load_lds_dwordx4 v[194:195], off
	s_add_i32 m0, s51, 0x2000
	s_add_u32 s52, s2, 0x40000
	v_lshl_add_u64 v[238:239], s[2:3], 0, v[130:131]
	s_addc_u32 s53, s3, 0
	s_add_i32 s51, s54, s34
	global_load_lds_dwordx4 v[238:239], off
	v_lshl_add_u64 v[240:241], s[52:53], 0, v[128:129]
	s_mov_b32 m0, s51
	v_lshl_add_u64 v[242:243], s[26:27], 0, v[132:133]
	global_load_lds_dwordx4 v[240:241], off
	v_lshl_add_u64 v[240:241], s[52:53], 0, v[130:131]
	s_add_i32 m0, s51, 0x2000
	s_nop 0
	global_load_lds_dwordx4 v[240:241], off
	v_lshl_add_u64 v[240:241], s[26:27], 0, v[134:135]
	s_mov_b32 m0, s35
	s_nop 0
	global_load_lds_dwordx4 v[240:241], off
	s_mov_b32 m0, s36
	s_nop 0
	global_load_lds_dwordx4 v[242:243], off
	s_waitcnt vmcnt(16)
	s_waitcnt lgkmcnt(0)
	s_barrier
	s_setprio 1
	s_waitcnt lgkmcnt(0)
	v_mfma_f32_16x16x32_bf16 v[60:63], v[140:143], v[190:193], 0
	v_mfma_f32_16x16x32_bf16 v[52:55], v[154:157], v[190:193], 0
	v_mfma_f32_16x16x32_bf16 v[44:47], v[140:143], v[214:217], 0
	v_mfma_f32_16x16x32_bf16 v[36:39], v[154:157], v[214:217], 0
	v_mfma_f32_16x16x32_bf16 v[28:31], v[140:143], v[222:225], 0
	v_mfma_f32_16x16x32_bf16 v[20:23], v[154:157], v[222:225], 0
	v_mfma_f32_16x16x32_bf16 v[12:15], v[140:143], v[230:233], 0
	v_mfma_f32_16x16x32_bf16 v[4:7], v[154:157], v[230:233], 0
	v_mfma_f32_16x16x32_bf16 v[60:63], v[150:153], v[210:213], v[60:63]
	v_mfma_f32_16x16x32_bf16 v[52:55], v[158:161], v[210:213], v[52:55]
	v_mfma_f32_16x16x32_bf16 v[44:47], v[150:153], v[218:221], v[44:47]
	v_mfma_f32_16x16x32_bf16 v[36:39], v[158:161], v[218:221], v[36:39]
	v_mfma_f32_16x16x32_bf16 v[28:31], v[150:153], v[226:229], v[28:31]
	v_mfma_f32_16x16x32_bf16 v[20:23], v[158:161], v[226:229], v[20:23]
	v_mfma_f32_16x16x32_bf16 v[12:15], v[150:153], v[234:237], v[12:15]
	v_mfma_f32_16x16x32_bf16 v[4:7], v[158:161], v[234:237], v[4:7]
	s_setprio 0
	s_setprio 1
	v_mfma_f32_16x16x32_bf16 v[56:59], v[174:177], v[190:193], 0
	v_mfma_f32_16x16x32_bf16 v[48:51], v[182:185], v[190:193], 0
	v_mfma_f32_16x16x32_bf16 v[40:43], v[174:177], v[214:217], 0
	v_mfma_f32_16x16x32_bf16 v[32:35], v[182:185], v[214:217], 0
	v_mfma_f32_16x16x32_bf16 v[24:27], v[174:177], v[222:225], 0
	v_mfma_f32_16x16x32_bf16 v[16:19], v[182:185], v[222:225], 0
	v_mfma_f32_16x16x32_bf16 v[8:11], v[174:177], v[230:233], 0
	v_mfma_f32_16x16x32_bf16 v[0:3], v[182:185], v[230:233], 0
	v_mfma_f32_16x16x32_bf16 v[56:59], v[178:181], v[210:213], v[56:59]
	v_mfma_f32_16x16x32_bf16 v[48:51], v[186:189], v[210:213], v[48:51]
	v_mfma_f32_16x16x32_bf16 v[40:43], v[178:181], v[218:221], v[40:43]
	v_mfma_f32_16x16x32_bf16 v[32:35], v[186:189], v[218:221], v[32:35]
	v_mfma_f32_16x16x32_bf16 v[24:27], v[178:181], v[226:229], v[24:27]
	v_mfma_f32_16x16x32_bf16 v[16:19], v[186:189], v[226:229], v[16:19]
	v_mfma_f32_16x16x32_bf16 v[8:11], v[178:181], v[234:237], v[8:11]
	v_mfma_f32_16x16x32_bf16 v[0:3], v[186:189], v[234:237], v[0:3]
	s_setprio 0
	s_barrier
	s_branch .Lpeel1_seg3

; __device__ __forceinline__ unsigned pk2(float lo, float hi) { unsigned r; asm("v_cvt_pk_bf16_f32 %0, %1, %2" : "=v"(r) : "v"(lo), "v"(hi)); return r; }
; __device__ __forceinline__ float silu_f(float x) { return x * sigmoid_f(x); }
;     __device__ __forceinline__ void operator()(const f32x4 (&acc)[2][2][4][2], const pg8::Unit& u, int wr, int wc, int fr, int fq) const {
;         const int row0 = u.pm * 256 + wr * 64 + fr, col0 = u.pn * 128 + wc * 32 + 8 * fq;
;         float rs[2][4];
; #pragma unroll
;         for (int ai = 0; ai < 2; ++ai)
; #pragma unroll
;             for (int m = 0; m < 4; ++m) rs[ai][m] = ss[row0 + ai * 128 + m * 16];
; #pragma unroll
;         for (int ai = 0; ai < 2; ++ai)
; #pragma unroll
;             for (int m = 0; m < 4; ++m) {
;                 const int r = row0 + ai * 128 + m * 16;
;                 const float rstd = __builtin_amdgcn_rsqf(rs[ai][m] * (1.0f / D) + EPS);
;                 float o[8];
; #pragma unroll
;                 for (int n = 0; n < 2; ++n)
; #pragma unroll
;                     for (int e = 0; e < 4; ++e) { const float g = acc[ai][0][m][n][e] * rstd, up = acc[ai][1][m][n][e] * rstd; o[4 * n + e] = silu_f(g) * up; }
;                 u32x4 w; w.x = pk2(o[0], o[1]); w.y = pk2(o[2], o[3]); w.z = pk2(o[4], o[5]); w.w = pk2(o[6], o[7]);
;                 *(u32x4*)(ACT + (size_t)r * FF + col0) = w;
.LBB0_526:
	s_lshl_b32 s2, s45, 8
	s_add_i32 s2, s2, s39
	v_add_u32_e32 v140, s2, v145
	v_lshlrev_b32_e32 v141, 2, v140
	v_mov_b32_e32 v150, v206
	v_mov_b32_e32 v152, v207
	v_mov_b32_e32 v154, v246
	v_mov_b32_e32 v156, v247
	v_mov_b32_e32 v158, v248
	v_mov_b32_e32 v160, v249
	v_mov_b32_e32 v144, v250
	v_mov_b32_e32 v174, v251
	s_lshl_b32 s2, s44, 7
	s_or_b32 s2, s2, s40
	v_lshl_add_u32 v142, v146, 3, s2
	s_movk_i32 s17, 0x1600
	v_mul_lo_u32 v171, v140, s17
	v_lshl_add_u32 v171, v142, 1, v171
	s_mov_b32 s2, 0xbfb8aa3b
	v_fmamk_f32 v150, v150, 0x3a800000, v199
	v_fmamk_f32 v152, v152, 0x3a800000, v199
	v_fmamk_f32 v154, v154, 0x3a800000, v199
	v_fmamk_f32 v156, v156, 0x3a800000, v199
	v_fmamk_f32 v158, v158, 0x3a800000, v199
	v_fmamk_f32 v160, v160, 0x3a800000, v199
	v_fmamk_f32 v144, v144, 0x3a800000, v199
	v_fmamk_f32 v174, v174, 0x3a800000, v199
	v_rsq_f32_e32 v150, v150
	v_rsq_f32_e32 v152, v152
	v_rsq_f32_e32 v154, v154
	v_rsq_f32_e32 v156, v156
	v_rsq_f32_e32 v158, v158
	v_rsq_f32_e32 v160, v160
	v_rsq_f32_e32 v144, v144
	v_rsq_f32_e32 v174, v174
	v_pk_mul_f32 v[124:125], v[124:125], v[150:151] op_sel_hi:[1,0]
	v_pk_mul_f32 v[120:121], v[120:121], v[150:151] op_sel_hi:[1,0]
	v_pk_mul_f32 v[126:127], v[126:127], v[150:151] op_sel_hi:[1,0]
	v_pk_mul_f32 v[122:123], v[122:123], v[150:151] op_sel_hi:[1,0]
	v_pk_mul_f32 v[140:141], v[124:125], s[2:3] op_sel_hi:[1,0]
	v_pk_mul_f32 v[142:143], v[126:127], s[2:3] op_sel_hi:[1,0]
	v_exp_f32_e32 v140, v140
	v_exp_f32_e32 v141, v141
	v_exp_f32_e32 v142, v142
	v_exp_f32_e32 v143, v143
	v_pk_add_f32 v[140:141], v[140:141], 1.0 op_sel_hi:[1,0]
	v_pk_add_f32 v[142:143], v[142:143], 1.0 op_sel_hi:[1,0]
	v_rcp_f32_e32 v140, v140
	v_rcp_f32_e32 v141, v141
	v_rcp_f32_e32 v142, v142
	v_rcp_f32_e32 v143, v143
	v_pk_mul_f32 v[124:125], v[124:125], v[140:141]
	v_pk_mul_f32 v[126:127], v[126:127], v[142:143]
	v_pk_mul_f32 v[124:125], v[124:125], v[120:121]
	v_pk_mul_f32 v[126:127], v[126:127], v[122:123]
	v_pk_mul_f32 v[116:117], v[116:117], v[150:151] op_sel_hi:[1,0]
	v_pk_mul_f32 v[112:113], v[112:113], v[150:151] op_sel_hi:[1,0]
	v_pk_mul_f32 v[118:119], v[118:119], v[150:151] op_sel_hi:[1,0]
	v_pk_mul_f32 v[114:115], v[114:115], v[150:151] op_sel_hi:[1,0]
	v_pk_mul_f32 v[140:141], v[116:117], s[2:3] op_sel_hi:[1,0]
	v_pk_mul_f32 v[142:143], v[118:119], s[2:3] op_sel_hi:[1,0]
	v_exp_f32_e32 v140, v140
	v_exp_f32_e32 v141, v141
	v_exp_f32_e32 v142, v142
	v_exp_f32_e32 v143, v143
	v_pk_add_f32 v[140:141], v[140:141], 1.0 op_sel_hi:[1,0]
	v_pk_add_f32 v[142:143], v[142:143], 1.0 op_sel_hi:[1,0]
	v_rcp_f32_e32 v140, v140
	v_rcp_f32_e32 v141, v141
	v_rcp_f32_e32 v142, v142
	v_rcp_f32_e32 v143, v143
	v_pk_mul_f32 v[116:117], v[116:117], v[140:141]
	v_pk_mul_f32 v[118:119], v[118:119], v[142:143]
	v_pk_mul_f32 v[116:117], v[116:117], v[112:113]
	v_pk_mul_f32 v[118:119], v[118:119], v[114:115]
	v_cvt_pk_bf16_f32 v124, v124, v125
	v_cvt_pk_bf16_f32 v125, v126, v127
	v_cvt_pk_bf16_f32 v126, v116, v117
	v_cvt_pk_bf16_f32 v127, v118, v119
	global_store_dwordx4 v171, v[124:127], s[10:11]
	v_pk_mul_f32 v[108:109], v[108:109], v[152:153] op_sel_hi:[1,0]
	v_pk_mul_f32 v[104:105], v[104:105], v[152:153] op_sel_hi:[1,0]
	v_pk_mul_f32 v[110:111], v[110:111], v[152:153] op_sel_hi:[1,0]
	v_pk_mul_f32 v[106:107], v[106:107], v[152:153] op_sel_hi:[1,0]
	v_pk_mul_f32 v[140:141], v[108:109], s[2:3] op_sel_hi:[1,0]
	v_pk_mul_f32 v[142:143], v[110:111], s[2:3] op_sel_hi:[1,0]
	v_exp_f32_e32 v140, v140
	v_exp_f32_e32 v141, v141
	v_exp_f32_e32 v142, v142
	v_exp_f32_e32 v143, v143
	v_pk_add_f32 v[140:141], v[140:141], 1.0 op_sel_hi:[1,0]
	v_pk_add_f32 v[142:143], v[142:143], 1.0 op_sel_hi:[1,0]
	v_rcp_f32_e32 v140, v140
	v_rcp_f32_e32 v141, v141
	v_rcp_f32_e32 v142, v142
	v_rcp_f32_e32 v143, v143
	v_pk_mul_f32 v[108:109], v[108:109], v[140:141]
	v_pk_mul_f32 v[110:111], v[110:111], v[142:143]
	v_pk_mul_f32 v[108:109], v[108:109], v[104:105]
	v_pk_mul_f32 v[110:111], v[110:111], v[106:107]
	v_pk_mul_f32 v[100:101], v[100:101], v[152:153] op_sel_hi:[1,0]
	v_pk_mul_f32 v[96:97], v[96:97], v[152:153] op_sel_hi:[1,0]
	v_pk_mul_f32 v[102:103], v[102:103], v[152:153] op_sel_hi:[1,0]
	v_pk_mul_f32 v[98:99], v[98:99], v[152:153] op_sel_hi:[1,0]
	v_pk_mul_f32 v[140:141], v[100:101], s[2:3] op_sel_hi:[1,0]
	v_pk_mul_f32 v[142:143], v[102:103], s[2:3] op_sel_hi:[1,0]
	v_exp_f32_e32 v140, v140
	v_exp_f32_e32 v141, v141
	v_exp_f32_e32 v142, v142
	v_exp_f32_e32 v143, v143
	v_pk_add_f32 v[140:141], v[140:141], 1.0 op_sel_hi:[1,0]
	v_pk_add_f32 v[142:143], v[142:143], 1.0 op_sel_hi:[1,0]
	v_rcp_f32_e32 v140, v140
	v_rcp_f32_e32 v141, v141
	v_rcp_f32_e32 v142, v142
	v_rcp_f32_e32 v143, v143
	v_pk_mul_f32 v[100:101], v[100:101], v[140:141]
	v_pk_mul_f32 v[102:103], v[102:103], v[142:143]
	v_pk_mul_f32 v[100:101], v[100:101], v[96:97]
	v_pk_mul_f32 v[102:103], v[102:103], v[98:99]
	v_cvt_pk_bf16_f32 v108, v108, v109
	v_cvt_pk_bf16_f32 v109, v110, v111
	v_cvt_pk_bf16_f32 v110, v100, v101
	v_cvt_pk_bf16_f32 v111, v102, v103
	v_add_u32_e32 v149, 0x16000, v171
	global_store_dwordx4 v149, v[108:111], s[10:11]
	v_pk_mul_f32 v[92:93], v[92:93], v[154:155] op_sel_hi:[1,0]
	v_pk_mul_f32 v[88:89], v[88:89], v[154:155] op_sel_hi:[1,0]
	v_pk_mul_f32 v[94:95], v[94:95], v[154:155] op_sel_hi:[1,0]
	v_pk_mul_f32 v[90:91], v[90:91], v[154:155] op_sel_hi:[1,0]
	v_pk_mul_f32 v[140:141], v[92:93], s[2:3] op_sel_hi:[1,0]
	v_pk_mul_f32 v[142:143], v[94:95], s[2:3] op_sel_hi:[1,0]
	v_exp_f32_e32 v140, v140
	v_exp_f32_e32 v141, v141
	v_exp_f32_e32 v142, v142
	v_exp_f32_e32 v143, v143
	v_pk_add_f32 v[140:141], v[140:141], 1.0 op_sel_hi:[1,0]
	v_pk_add_f32 v[142:143], v[142:143], 1.0 op_sel_hi:[1,0]
; __device__ __forceinline__ unsigned pk2(float lo, float hi) { unsigned r; asm("v_cvt_pk_bf16_f32 %0, %1, %2" : "=v"(r) : "v"(lo), "v"(hi)); return r; }
; __device__ __forceinline__ float silu_f(float x) { return x * sigmoid_f(x); }
;     __device__ __forceinline__ void operator()(const f32x4 (&acc)[2][2][4][2], const pg8::Unit& u, int wr, int wc, int fr, int fq) const {
;     ...
;         for (int ai = 0; ai < 2; ++ai)
; #pragma unroll
;             for (int m = 0; m < 4; ++m) {
;                 const int r = row0 + ai * 128 + m * 16;
;                 const float rstd = __builtin_amdgcn_rsqf(rs[ai][m] * (1.0f / D) + EPS);
;                 float o[8];
; #pragma unroll
;                 for (int n = 0; n < 2; ++n)
; #pragma unroll
;                     for (int e = 0; e < 4; ++e) { const float g = acc[ai][0][m][n][e] * rstd, up = acc[ai][1][m][n][e] * rstd; o[4 * n + e] = silu_f(g) * up; }
;                 u32x4 w; w.x = pk2(o[0], o[1]); w.y = pk2(o[2], o[3]); w.z = pk2(o[4], o[5]); w.w = pk2(o[6], o[7]);
;                 *(u32x4*)(ACT + (size_t)r * FF + col0) = w;
	v_rcp_f32_e32 v140, v140
	v_rcp_f32_e32 v141, v141
	v_rcp_f32_e32 v142, v142
	v_rcp_f32_e32 v143, v143
	v_pk_mul_f32 v[92:93], v[92:93], v[140:141]
	v_pk_mul_f32 v[94:95], v[94:95], v[142:143]
	v_pk_mul_f32 v[92:93], v[92:93], v[88:89]
	v_pk_mul_f32 v[94:95], v[94:95], v[90:91]
	v_pk_mul_f32 v[84:85], v[84:85], v[154:155] op_sel_hi:[1,0]
	v_pk_mul_f32 v[80:81], v[80:81], v[154:155] op_sel_hi:[1,0]
	v_pk_mul_f32 v[86:87], v[86:87], v[154:155] op_sel_hi:[1,0]
	v_pk_mul_f32 v[82:83], v[82:83], v[154:155] op_sel_hi:[1,0]
	v_pk_mul_f32 v[140:141], v[84:85], s[2:3] op_sel_hi:[1,0]
	v_pk_mul_f32 v[142:143], v[86:87], s[2:3] op_sel_hi:[1,0]
	v_exp_f32_e32 v140, v140
	v_exp_f32_e32 v141, v141
	v_exp_f32_e32 v142, v142
	v_exp_f32_e32 v143, v143
	v_pk_add_f32 v[140:141], v[140:141], 1.0 op_sel_hi:[1,0]
	v_pk_add_f32 v[142:143], v[142:143], 1.0 op_sel_hi:[1,0]
	v_rcp_f32_e32 v140, v140
	v_rcp_f32_e32 v141, v141
	v_rcp_f32_e32 v142, v142
	v_rcp_f32_e32 v143, v143
	v_pk_mul_f32 v[84:85], v[84:85], v[140:141]
	v_pk_mul_f32 v[86:87], v[86:87], v[142:143]
	v_pk_mul_f32 v[84:85], v[84:85], v[80:81]
	v_pk_mul_f32 v[86:87], v[86:87], v[82:83]
	v_cvt_pk_bf16_f32 v92, v92, v93
	v_cvt_pk_bf16_f32 v93, v94, v95
	v_cvt_pk_bf16_f32 v94, v84, v85
	v_cvt_pk_bf16_f32 v95, v86, v87
	v_add_u32_e32 v149, 0x2c000, v171
	global_store_dwordx4 v149, v[92:95], s[10:11]
	v_pk_mul_f32 v[76:77], v[76:77], v[156:157] op_sel_hi:[1,0]
	v_pk_mul_f32 v[72:73], v[72:73], v[156:157] op_sel_hi:[1,0]
	v_pk_mul_f32 v[78:79], v[78:79], v[156:157] op_sel_hi:[1,0]
	v_pk_mul_f32 v[74:75], v[74:75], v[156:157] op_sel_hi:[1,0]
	v_pk_mul_f32 v[140:141], v[76:77], s[2:3] op_sel_hi:[1,0]
	v_pk_mul_f32 v[142:143], v[78:79], s[2:3] op_sel_hi:[1,0]
	v_exp_f32_e32 v140, v140
	v_exp_f32_e32 v141, v141
	v_exp_f32_e32 v142, v142
	v_exp_f32_e32 v143, v143
	v_pk_add_f32 v[140:141], v[140:141], 1.0 op_sel_hi:[1,0]
	v_pk_add_f32 v[142:143], v[142:143], 1.0 op_sel_hi:[1,0]
	v_rcp_f32_e32 v140, v140
	v_rcp_f32_e32 v141, v141
	v_rcp_f32_e32 v142, v142
	v_rcp_f32_e32 v143, v143
	v_pk_mul_f32 v[76:77], v[76:77], v[140:141]
	v_pk_mul_f32 v[78:79], v[78:79], v[142:143]
	v_pk_mul_f32 v[76:77], v[76:77], v[72:73]
	v_pk_mul_f32 v[78:79], v[78:79], v[74:75]
	v_pk_mul_f32 v[68:69], v[68:69], v[156:157] op_sel_hi:[1,0]
	v_pk_mul_f32 v[64:65], v[64:65], v[156:157] op_sel_hi:[1,0]
	v_pk_mul_f32 v[70:71], v[70:71], v[156:157] op_sel_hi:[1,0]
	v_pk_mul_f32 v[66:67], v[66:67], v[156:157] op_sel_hi:[1,0]
	v_pk_mul_f32 v[140:141], v[68:69], s[2:3] op_sel_hi:[1,0]
	v_pk_mul_f32 v[142:143], v[70:71], s[2:3] op_sel_hi:[1,0]
	v_exp_f32_e32 v140, v140
	v_exp_f32_e32 v141, v141
	v_exp_f32_e32 v142, v142
	v_exp_f32_e32 v143, v143
	v_pk_add_f32 v[140:141], v[140:141], 1.0 op_sel_hi:[1,0]
	v_pk_add_f32 v[142:143], v[142:143], 1.0 op_sel_hi:[1,0]
	v_rcp_f32_e32 v140, v140
	v_rcp_f32_e32 v141, v141
	v_rcp_f32_e32 v142, v142
	v_rcp_f32_e32 v143, v143
	v_pk_mul_f32 v[68:69], v[68:69], v[140:141]
	v_pk_mul_f32 v[70:71], v[70:71], v[142:143]
	v_pk_mul_f32 v[68:69], v[68:69], v[64:65]
	v_pk_mul_f32 v[70:71], v[70:71], v[66:67]
	v_cvt_pk_bf16_f32 v76, v76, v77
	v_cvt_pk_bf16_f32 v77, v78, v79
	v_cvt_pk_bf16_f32 v78, v68, v69
	v_cvt_pk_bf16_f32 v79, v70, v71
	v_add_u32_e32 v149, 0x42000, v171
	global_store_dwordx4 v149, v[76:79], s[10:11]
	v_pk_mul_f32 v[60:61], v[60:61], v[158:159] op_sel_hi:[1,0]
	v_pk_mul_f32 v[56:57], v[56:57], v[158:159] op_sel_hi:[1,0]
	v_pk_mul_f32 v[62:63], v[62:63], v[158:159] op_sel_hi:[1,0]
	v_pk_mul_f32 v[58:59], v[58:59], v[158:159] op_sel_hi:[1,0]
	v_pk_mul_f32 v[140:141], v[60:61], s[2:3] op_sel_hi:[1,0]
	v_pk_mul_f32 v[142:143], v[62:63], s[2:3] op_sel_hi:[1,0]
	v_exp_f32_e32 v140, v140
	v_exp_f32_e32 v141, v141
	v_exp_f32_e32 v142, v142
	v_exp_f32_e32 v143, v143
	v_pk_add_f32 v[140:141], v[140:141], 1.0 op_sel_hi:[1,0]
	v_pk_add_f32 v[142:143], v[142:143], 1.0 op_sel_hi:[1,0]
	v_rcp_f32_e32 v140, v140
	v_rcp_f32_e32 v141, v141
	v_rcp_f32_e32 v142, v142
	v_rcp_f32_e32 v143, v143
	v_pk_mul_f32 v[60:61], v[60:61], v[140:141]
	v_pk_mul_f32 v[62:63], v[62:63], v[142:143]
	v_pk_mul_f32 v[60:61], v[60:61], v[56:57]
	v_pk_mul_f32 v[62:63], v[62:63], v[58:59]
	v_pk_mul_f32 v[52:53], v[52:53], v[158:159] op_sel_hi:[1,0]
	v_pk_mul_f32 v[48:49], v[48:49], v[158:159] op_sel_hi:[1,0]
	v_pk_mul_f32 v[54:55], v[54:55], v[158:159] op_sel_hi:[1,0]
	v_pk_mul_f32 v[50:51], v[50:51], v[158:159] op_sel_hi:[1,0]
	v_pk_mul_f32 v[140:141], v[52:53], s[2:3] op_sel_hi:[1,0]
	v_pk_mul_f32 v[142:143], v[54:55], s[2:3] op_sel_hi:[1,0]
	v_exp_f32_e32 v140, v140
	v_exp_f32_e32 v141, v141
	v_exp_f32_e32 v142, v142
	v_exp_f32_e32 v143, v143
	v_pk_add_f32 v[140:141], v[140:141], 1.0 op_sel_hi:[1,0]
	v_pk_add_f32 v[142:143], v[142:143], 1.0 op_sel_hi:[1,0]
	v_rcp_f32_e32 v140, v140
	v_rcp_f32_e32 v141, v141
	v_rcp_f32_e32 v142, v142
	v_rcp_f32_e32 v143, v143
	v_pk_mul_f32 v[52:53], v[52:53], v[140:141]
	v_pk_mul_f32 v[54:55], v[54:55], v[142:143]
	v_pk_mul_f32 v[52:53], v[52:53], v[48:49]
	v_pk_mul_f32 v[54:55], v[54:55], v[50:51]
	v_cvt_pk_bf16_f32 v60, v60, v61
	v_cvt_pk_bf16_f32 v61, v62, v63
	v_cvt_pk_bf16_f32 v62, v52, v53
	v_cvt_pk_bf16_f32 v63, v54, v55
	v_add_u32_e32 v149, 0xb0000, v171
	global_store_dwordx4 v149, v[60:63], s[10:11]
	v_pk_mul_f32 v[44:45], v[44:45], v[160:161] op_sel_hi:[1,0]
	v_pk_mul_f32 v[40:41], v[40:41], v[160:161] op_sel_hi:[1,0]
	v_pk_mul_f32 v[46:47], v[46:47], v[160:161] op_sel_hi:[1,0]
	v_pk_mul_f32 v[42:43], v[42:43], v[160:161] op_sel_hi:[1,0]
	v_pk_mul_f32 v[140:141], v[44:45], s[2:3] op_sel_hi:[1,0]
	v_pk_mul_f32 v[142:143], v[46:47], s[2:3] op_sel_hi:[1,0]
; #define PG8_BAR __builtin_amdgcn_s_barrier()
; #define PG8_ZERO_ACC() do { _Pragma("unroll") for (int a = 0; a < 2; ++a) _Pragma("unroll") for (int b = 0; b < 2; ++b) _Pragma("unroll") for (int m = 0; m < 4; ++m) _Pragma("unroll") for (int n = 0; n < 2; ++n) acc[a][b][m][n] = (f32x4){0.f, 0.f, 0.f, 0.f}; } while (0)
; __device__ __forceinline__ unsigned pk2(float lo, float hi) { unsigned r; asm("v_cvt_pk_bf16_f32 %0, %1, %2" : "=v"(r) : "v"(lo), "v"(hi)); return r; }
; __device__ __forceinline__ float silu_f(float x) { return x * sigmoid_f(x); }
; template <class Epi, class Sched, bool ALIGN_EPI = false, bool SP2 = false>
; __device__ __forceinline__ void gemm_phase(PG8_LAS unsigned char* lds, const Gemm g, const Sched& S, const Epi& E, const int wave_s) {
;     ...
;         if (!has_next) break;
;     ...
;         if constexpr (Epi::INIT_ACC) {
;             if (Sched::STREAMK && nxt.kind == 2) S.load_partial(acc, tid, wid, lane);
;             else if (nxt.kind == 0) { int fr_i = fr, fq_i = fq; asm volatile("" : "+v"(fr_i), "+v"(fq_i)); E.init(acc, nxt, wr, wc, fr_i, fq_i); }
;             else PG8_ZERO_ACC();
;         } else {
;             if (Sched::STREAMK && nxt.kind == 2) S.load_partial(acc, tid, wid, lane);
;             else PG8_ZERO_ACC();
;         }
;     ...
;         cur = nxt; cA = nA; cB = nB; ++ui;
;         if constexpr (ALIGN_EPI) { if (wr == 1) PG8_BAR; }
;     __device__ __forceinline__ void operator()(const f32x4 (&acc)[2][2][4][2], const pg8::Unit& u, int wr, int wc, int fr, int fq) const {
;     ...
;         for (int ai = 0; ai < 2; ++ai)
; #pragma unroll
;             for (int m = 0; m < 4; ++m) {
;                 const int r = row0 + ai * 128 + m * 16;
;                 const float rstd = __builtin_amdgcn_rsqf(rs[ai][m] * (1.0f / D) + EPS);
;                 float o[8];
; #pragma unroll
;                 for (int n = 0; n < 2; ++n)
; #pragma unroll
;                     for (int e = 0; e < 4; ++e) { const float g = acc[ai][0][m][n][e] * rstd, up = acc[ai][1][m][n][e] * rstd; o[4 * n + e] = silu_f(g) * up; }
;                 u32x4 w; w.x = pk2(o[0], o[1]); w.y = pk2(o[2], o[3]); w.z = pk2(o[4], o[5]); w.w = pk2(o[6], o[7]);
;                 *(u32x4*)(ACT + (size_t)r * FF + col0) = w;
	v_exp_f32_e32 v140, v140
	v_exp_f32_e32 v141, v141
	v_exp_f32_e32 v142, v142
	v_exp_f32_e32 v143, v143
	v_pk_add_f32 v[140:141], v[140:141], 1.0 op_sel_hi:[1,0]
	v_pk_add_f32 v[142:143], v[142:143], 1.0 op_sel_hi:[1,0]
	v_rcp_f32_e32 v140, v140
	v_rcp_f32_e32 v141, v141
	v_rcp_f32_e32 v142, v142
	v_rcp_f32_e32 v143, v143
	v_pk_mul_f32 v[44:45], v[44:45], v[140:141]
	v_pk_mul_f32 v[46:47], v[46:47], v[142:143]
	v_pk_mul_f32 v[44:45], v[44:45], v[40:41]
	v_pk_mul_f32 v[46:47], v[46:47], v[42:43]
	v_pk_mul_f32 v[36:37], v[36:37], v[160:161] op_sel_hi:[1,0]
	v_pk_mul_f32 v[32:33], v[32:33], v[160:161] op_sel_hi:[1,0]
	v_pk_mul_f32 v[38:39], v[38:39], v[160:161] op_sel_hi:[1,0]
	v_pk_mul_f32 v[34:35], v[34:35], v[160:161] op_sel_hi:[1,0]
	v_pk_mul_f32 v[140:141], v[36:37], s[2:3] op_sel_hi:[1,0]
	v_pk_mul_f32 v[142:143], v[38:39], s[2:3] op_sel_hi:[1,0]
	v_exp_f32_e32 v140, v140
	v_exp_f32_e32 v141, v141
	v_exp_f32_e32 v142, v142
	v_exp_f32_e32 v143, v143
	v_pk_add_f32 v[140:141], v[140:141], 1.0 op_sel_hi:[1,0]
	v_pk_add_f32 v[142:143], v[142:143], 1.0 op_sel_hi:[1,0]
	v_rcp_f32_e32 v140, v140
	v_rcp_f32_e32 v141, v141
	v_rcp_f32_e32 v142, v142
	v_rcp_f32_e32 v143, v143
	v_pk_mul_f32 v[36:37], v[36:37], v[140:141]
	v_pk_mul_f32 v[38:39], v[38:39], v[142:143]
	v_pk_mul_f32 v[36:37], v[36:37], v[32:33]
	v_pk_mul_f32 v[38:39], v[38:39], v[34:35]
	v_cvt_pk_bf16_f32 v44, v44, v45
	v_cvt_pk_bf16_f32 v45, v46, v47
	v_cvt_pk_bf16_f32 v46, v36, v37
	v_cvt_pk_bf16_f32 v47, v38, v39
	v_add_u32_e32 v149, 0xc6000, v171
	global_store_dwordx4 v149, v[44:47], s[10:11]
	v_pk_mul_f32 v[28:29], v[28:29], v[144:145] op_sel_hi:[1,0]
	v_pk_mul_f32 v[24:25], v[24:25], v[144:145] op_sel_hi:[1,0]
	v_pk_mul_f32 v[30:31], v[30:31], v[144:145] op_sel_hi:[1,0]
	v_pk_mul_f32 v[26:27], v[26:27], v[144:145] op_sel_hi:[1,0]
	v_pk_mul_f32 v[140:141], v[28:29], s[2:3] op_sel_hi:[1,0]
	v_pk_mul_f32 v[142:143], v[30:31], s[2:3] op_sel_hi:[1,0]
	v_exp_f32_e32 v140, v140
	v_exp_f32_e32 v141, v141
	v_exp_f32_e32 v142, v142
	v_exp_f32_e32 v143, v143
	v_pk_add_f32 v[140:141], v[140:141], 1.0 op_sel_hi:[1,0]
	v_pk_add_f32 v[142:143], v[142:143], 1.0 op_sel_hi:[1,0]
	v_rcp_f32_e32 v140, v140
	v_rcp_f32_e32 v141, v141
	v_rcp_f32_e32 v142, v142
	v_rcp_f32_e32 v143, v143
	v_pk_mul_f32 v[28:29], v[28:29], v[140:141]
	v_pk_mul_f32 v[30:31], v[30:31], v[142:143]
	v_pk_mul_f32 v[28:29], v[28:29], v[24:25]
	v_pk_mul_f32 v[30:31], v[30:31], v[26:27]
	v_pk_mul_f32 v[20:21], v[20:21], v[144:145] op_sel_hi:[1,0]
	v_pk_mul_f32 v[16:17], v[16:17], v[144:145] op_sel_hi:[1,0]
	v_pk_mul_f32 v[22:23], v[22:23], v[144:145] op_sel_hi:[1,0]
	v_pk_mul_f32 v[18:19], v[18:19], v[144:145] op_sel_hi:[1,0]
	v_pk_mul_f32 v[140:141], v[20:21], s[2:3] op_sel_hi:[1,0]
	v_pk_mul_f32 v[142:143], v[22:23], s[2:3] op_sel_hi:[1,0]
	v_exp_f32_e32 v140, v140
	v_exp_f32_e32 v141, v141
	v_exp_f32_e32 v142, v142
	v_exp_f32_e32 v143, v143
	v_pk_add_f32 v[140:141], v[140:141], 1.0 op_sel_hi:[1,0]
	v_pk_add_f32 v[142:143], v[142:143], 1.0 op_sel_hi:[1,0]
	v_rcp_f32_e32 v140, v140
	v_rcp_f32_e32 v141, v141
	v_rcp_f32_e32 v142, v142
	v_rcp_f32_e32 v143, v143
	v_pk_mul_f32 v[20:21], v[20:21], v[140:141]
	v_pk_mul_f32 v[22:23], v[22:23], v[142:143]
	v_pk_mul_f32 v[20:21], v[20:21], v[16:17]
	v_pk_mul_f32 v[22:23], v[22:23], v[18:19]
	v_cvt_pk_bf16_f32 v28, v28, v29
	v_cvt_pk_bf16_f32 v29, v30, v31
	v_cvt_pk_bf16_f32 v30, v20, v21
	v_cvt_pk_bf16_f32 v31, v22, v23
	v_add_u32_e32 v149, 0xdc000, v171
	global_store_dwordx4 v149, v[28:31], s[10:11]
	v_pk_mul_f32 v[12:13], v[12:13], v[174:175] op_sel_hi:[1,0]
	v_pk_mul_f32 v[8:9], v[8:9], v[174:175] op_sel_hi:[1,0]
	v_pk_mul_f32 v[14:15], v[14:15], v[174:175] op_sel_hi:[1,0]
	v_pk_mul_f32 v[10:11], v[10:11], v[174:175] op_sel_hi:[1,0]
	v_pk_mul_f32 v[140:141], v[12:13], s[2:3] op_sel_hi:[1,0]
	v_pk_mul_f32 v[142:143], v[14:15], s[2:3] op_sel_hi:[1,0]
	v_exp_f32_e32 v140, v140
	v_exp_f32_e32 v141, v141
	v_exp_f32_e32 v142, v142
	v_exp_f32_e32 v143, v143
	v_pk_add_f32 v[140:141], v[140:141], 1.0 op_sel_hi:[1,0]
	v_pk_add_f32 v[142:143], v[142:143], 1.0 op_sel_hi:[1,0]
	v_rcp_f32_e32 v140, v140
	v_rcp_f32_e32 v141, v141
	v_rcp_f32_e32 v142, v142
	v_rcp_f32_e32 v143, v143
	v_pk_mul_f32 v[12:13], v[12:13], v[140:141]
	v_pk_mul_f32 v[14:15], v[14:15], v[142:143]
	v_pk_mul_f32 v[12:13], v[12:13], v[8:9]
	v_pk_mul_f32 v[14:15], v[14:15], v[10:11]
	v_pk_mul_f32 v[4:5], v[4:5], v[174:175] op_sel_hi:[1,0]
	v_pk_mul_f32 v[0:1], v[0:1], v[174:175] op_sel_hi:[1,0]
	v_pk_mul_f32 v[6:7], v[6:7], v[174:175] op_sel_hi:[1,0]
	v_pk_mul_f32 v[2:3], v[2:3], v[174:175] op_sel_hi:[1,0]
	v_pk_mul_f32 v[140:141], v[4:5], s[2:3] op_sel_hi:[1,0]
	v_pk_mul_f32 v[142:143], v[6:7], s[2:3] op_sel_hi:[1,0]
	v_exp_f32_e32 v140, v140
	v_exp_f32_e32 v141, v141
	v_exp_f32_e32 v142, v142
	v_exp_f32_e32 v143, v143
	v_pk_add_f32 v[140:141], v[140:141], 1.0 op_sel_hi:[1,0]
	v_pk_add_f32 v[142:143], v[142:143], 1.0 op_sel_hi:[1,0]
	v_rcp_f32_e32 v140, v140
	v_rcp_f32_e32 v141, v141
	v_rcp_f32_e32 v142, v142
	v_rcp_f32_e32 v143, v143
	v_pk_mul_f32 v[4:5], v[4:5], v[140:141]
	v_pk_mul_f32 v[6:7], v[6:7], v[142:143]
	v_pk_mul_f32 v[4:5], v[4:5], v[0:1]
	v_pk_mul_f32 v[6:7], v[6:7], v[2:3]
	v_cvt_pk_bf16_f32 v12, v12, v13
	v_cvt_pk_bf16_f32 v13, v14, v15
	v_cvt_pk_bf16_f32 v14, v4, v5
	v_cvt_pk_bf16_f32 v15, v6, v7
	v_add_u32_e32 v149, 0xf2000, v171
	global_store_dwordx4 v149, v[12:15], s[10:11]
	s_mov_b64 s[2:3], -1
	s_andn2_b64 vcc, exec, s[6:7]
	s_cbranch_vccnz .LBB0_515
	s_andn2_b64 vcc, exec, s[8:9]
	s_cbranch_vccnz .LBB0_514
	s_barrier
	s_branch .LBB0_514
